# E66: E65 minus the redundant vmcnt(0) ahead of the counted staging-write waits in both MLA tile copies
# speedup vs baseline: 1.0082x; 1.0040x over previous
; #define PK4(P, BASE, OUT) do { u32x4 w = {cvtb(P[BASE + 0], P[BASE + 1]), cvtb(P[BASE + 2], P[BASE + 3]), \
;     cvtb(P[BASE + 4], P[BASE + 5]), cvtb(P[BASE + 6], P[BASE + 7])}; OUT = *reinterpret_cast<bf16x8*>(&w); } while (0)
; __device__ __forceinline__ void finishSM(f32x16& p0, f32x16& p1, float alpha, float& l_reg, bf16x8& pa0, bf16x8& pa1, bf16x8& pa2, bf16x8& pa3) {
; #pragma unroll
;   for (int r = 0; r < 16; ++r) p1[r] = __builtin_amdgcn_exp2f(p1[r]);
;   float ps = 0;
; #pragma unroll
;   for (int r = 0; r < 16; ++r) ps += p0[r];
; #pragma unroll
;   for (int r = 0; r < 16; ++r) ps += p1[r];
;   { auto rr = __builtin_amdgcn_permlane32_swap(__float_as_uint(ps), __float_as_uint(ps), false, false);
;     ps = __uint_as_float(rr[0]) + __uint_as_float(rr[1]); }
;   l_reg = l_reg * alpha + ps;
;     ...
;   PK4(p0, 0, pa0); PK4(p0, 8, pa1); PK4(p1, 0, pa2); PK4(p1, 8, pa3);
;     ...
; }
; template <int NQK>
; __device__ __forceinline__ void qkt(f32x16& p0, f32x16& p1, const char* Ks, const bf16x8* qr, int r32, int hi) {
;   constexpr int KROW = NQK * 32 + 16;
;   p0 = f32x16{}; p1 = f32x16{};
; #pragma unroll
;   for (int d0 = 0; d0 < NQK; ++d0) { const int cb = (d0 * 16 + hi * 8) * 2;
;     bf16x8 b0 = *reinterpret_cast<const bf16x8*>(Ks + r32 * KROW + cb);
;     bf16x8 b1 = *reinterpret_cast<const bf16x8*>(Ks + (32 + r32) * KROW + cb);
;     p0 = __builtin_amdgcn_mfma_f32_32x32x16_bf16(b0, qr[d0], p0, 0, 0, 0);
;     p1 = __builtin_amdgcn_mfma_f32_32x32x16_bf16(b1, qr[d0], p1, 0, 0, 0); }
; }
.LBB0_2539:
	s_mov_b32 s14, s44
	s_mov_b32 s44, s8
	s_mul_i32 s8, s14, 0x6400
	v_add_u32_e32 v169, s8, v174
	ds_read_b128 v[64:67], v169 offset:61952
	ds_read_b128 v[68:71], v169 offset:49152
	ds_read_b128 v[180:183], v169 offset:49184
	ds_read_b128 v[222:225], v169 offset:61984
	v_exp_f32_e32 v231, v146
	v_add_f32_e32 v146, 0, v184
	s_waitcnt lgkmcnt(2)
	v_mfma_f32_32x32x16_bf16 v[80:95], v[68:71], v[140:143], 0
	v_add_f32_e32 v146, v185, v146
	v_add_f32_e32 v146, v189, v146
	v_add_f32_e32 v146, v191, v146
	v_add_f32_e32 v146, v198, v146
	v_add_f32_e32 v146, v200, v146
	v_add_f32_e32 v146, v214, v146
	v_add_f32_e32 v146, v217, v146
	v_mfma_f32_32x32x16_bf16 v[64:79], v[64:67], v[140:143], 0
	v_add_f32_e32 v146, v215, v146
	v_add_f32_e32 v146, v218, v146
	v_add_f32_e32 v146, v199, v146
	v_add_f32_e32 v146, v201, v146
	v_add_f32_e32 v146, v216, v146
	v_add_f32_e32 v146, v219, v146
	v_add_f32_e32 v146, v220, v146
	s_waitcnt lgkmcnt(1)
	v_mfma_f32_32x32x16_bf16 v[80:95], v[180:183], v[136:139], v[80:95]
	v_add_f32_e32 v146, v221, v146
	v_exp_f32_e32 v229, v150
	v_exp_f32_e32 v226, v155
	v_exp_f32_e32 v227, v152
	v_exp_f32_e32 v228, v153
	v_exp_f32_e32 v230, v151
	v_exp_f32_e32 v148, v148
	s_waitcnt lgkmcnt(0)
	v_mfma_f32_32x32x16_bf16 v[64:79], v[222:225], v[136:139], v[64:79]
	ds_read_b128 v[180:183], v169 offset:49216
	ds_read_b128 v[222:225], v169 offset:62016
	v_exp_f32_e32 v149, v149
	v_exp_f32_e32 v232, v147
	v_cvt_pk_bf16_f32 v155, v199, v201
	v_cvt_pk_bf16_f32 v147, v229, v230
	s_waitcnt lgkmcnt(1)
	v_mfma_f32_32x32x16_bf16 v[80:95], v[180:183], v[132:135], v[80:95]
	s_waitcnt lgkmcnt(0)
	v_mfma_f32_32x32x16_bf16 v[64:79], v[222:225], v[132:135], v[64:79]
	ds_read_b128 v[180:183], v169 offset:49248
	ds_read_b128 v[222:225], v169 offset:62048
	s_waitcnt lgkmcnt(1)
	v_mfma_f32_32x32x16_bf16 v[80:95], v[180:183], v[128:131], v[80:95]
	s_waitcnt lgkmcnt(0)
	v_mfma_f32_32x32x16_bf16 v[64:79], v[222:225], v[128:131], v[64:79]
	ds_read_b128 v[180:183], v169 offset:49280
	ds_read_b128 v[222:225], v169 offset:62080
	s_waitcnt lgkmcnt(1)
	v_mfma_f32_32x32x16_bf16 v[80:95], v[180:183], v[124:127], v[80:95]
	s_waitcnt lgkmcnt(0)
	v_mfma_f32_32x32x16_bf16 v[64:79], v[222:225], v[124:127], v[64:79]
	ds_read_b128 v[180:183], v169 offset:49312
	ds_read_b128 v[222:225], v169 offset:62112
	s_waitcnt lgkmcnt(1)
	v_mfma_f32_32x32x16_bf16 v[80:95], v[180:183], v[120:123], v[80:95]
	s_waitcnt lgkmcnt(0)
	v_mfma_f32_32x32x16_bf16 v[64:79], v[222:225], v[120:123], v[64:79]
	ds_read_b128 v[180:183], v169 offset:49344
	ds_read_b128 v[222:225], v169 offset:62144
	s_waitcnt lgkmcnt(1)
	v_mfma_f32_32x32x16_bf16 v[80:95], v[180:183], v[116:119], v[80:95]
	s_waitcnt lgkmcnt(0)
	v_mfma_f32_32x32x16_bf16 v[64:79], v[222:225], v[116:119], v[64:79]
	ds_read_b128 v[180:183], v169 offset:49376
	ds_read_b128 v[222:225], v169 offset:62176
	s_waitcnt lgkmcnt(1)
	v_mfma_f32_32x32x16_bf16 v[80:95], v[180:183], v[112:115], v[80:95]
	s_waitcnt lgkmcnt(0)
	v_mfma_f32_32x32x16_bf16 v[64:79], v[222:225], v[112:115], v[64:79]
	ds_read_b128 v[180:183], v169 offset:49408
	ds_read_b128 v[222:225], v169 offset:62208
	s_waitcnt lgkmcnt(1)
	v_mfma_f32_32x32x16_bf16 v[80:95], v[180:183], v[108:111], v[80:95]
	s_waitcnt lgkmcnt(0)
	v_mfma_f32_32x32x16_bf16 v[64:79], v[222:225], v[108:111], v[64:79]
	ds_read_b128 v[180:183], v169 offset:49440
	ds_read_b128 v[222:225], v169 offset:62240
	s_waitcnt lgkmcnt(1)
	v_mfma_f32_32x32x16_bf16 v[80:95], v[180:183], v[104:107], v[80:95]
	s_waitcnt lgkmcnt(0)
	v_mfma_f32_32x32x16_bf16 v[64:79], v[222:225], v[104:107], v[64:79]
	ds_read_b128 v[180:183], v169 offset:49472
	ds_read_b128 v[222:225], v169 offset:62272
	s_waitcnt lgkmcnt(1)
	v_mfma_f32_32x32x16_bf16 v[80:95], v[180:183], v[100:103], v[80:95]
	s_waitcnt lgkmcnt(0)
	v_mfma_f32_32x32x16_bf16 v[64:79], v[222:225], v[100:103], v[64:79]
	ds_read_b128 v[180:183], v169 offset:49504
	ds_read_b128 v[222:225], v169 offset:62304
	v_exp_f32_e32 v169, v160
	v_cvt_pk_bf16_f32 v160, v198, v200
	v_add_f32_e32 v146, v169, v146
	s_waitcnt lgkmcnt(1)
	v_mfma_f32_32x32x16_bf16 v[80:95], v[180:183], v[96:99], v[80:95]
	v_exp_f32_e32 v180, v161
	v_exp_f32_e32 v183, v158
	v_cvt_pk_bf16_f32 v158, v184, v185
	v_cvt_pk_bf16_f32 v161, v214, v217
	v_add_f32_e32 v146, v180, v146
	v_cvt_pk_bf16_f32 v150, v169, v180
	v_add_f32_e32 v146, v183, v146
	s_nop 4
	v_max_f32_e32 v169, v81, v81
	v_max_f32_e32 v180, v80, v80
	s_waitcnt lgkmcnt(0)
; #define SBAR() __builtin_amdgcn_sched_barrier(0)
; __device__ __forceinline__ void decideSM(const f32x16& p0, const f32x16& p1, float& m_reg, float& mn, float& alpha, const float C, const float thr) {
;   float pmax = p0[0];
; #pragma unroll
;   for (int r = 1; r < 16; ++r) pmax = fmaxf(pmax, p0[r]);
; #pragma unroll
;   for (int r = 0; r < 16; ++r) pmax = fmaxf(pmax, p1[r]);
;   { auto rr = __builtin_amdgcn_permlane32_swap(__float_as_uint(pmax), __float_as_uint(pmax), false, false);
;     pmax = fmaxf(__uint_as_float(rr[0]), __uint_as_float(rr[1])); }
;   if (__builtin_expect(__all(pmax - m_reg <= thr), 1)) { mn = m_reg; alpha = 1.f; }
;   else { mn = fmaxf(m_reg, pmax); alpha = __builtin_amdgcn_exp2f((m_reg - mn) * C); m_reg = mn; }
; }
; __device__ __forceinline__ void finishSM(f32x16& p0, f32x16& p1, float alpha, float& l_reg, bf16x8& pa0, bf16x8& pa1, bf16x8& pa2, bf16x8& pa3) {
; #pragma unroll
;   for (int r = 0; r < 16; ++r) p1[r] = __builtin_amdgcn_exp2f(p1[r]);
;   float ps = 0;
; #pragma unroll
;   for (int r = 0; r < 16; ++r) ps += p0[r];
; #pragma unroll
;   for (int r = 0; r < 16; ++r) ps += p1[r];
;   { auto rr = __builtin_amdgcn_permlane32_swap(__float_as_uint(ps), __float_as_uint(ps), false, false);
;     ps = __uint_as_float(rr[0]) + __uint_as_float(rr[1]); }
;   l_reg = l_reg * alpha + ps;
;     ...
;   PK4(p0, 0, pa0); PK4(p0, 8, pa1); PK4(p1, 0, pa2); PK4(p1, 8, pa3);
;     ...
; }
; template <int NQK, int SD, bool MI> ...
;     ...
;   f32x16 pA0, pA1, pB0, pB1; float mnA, mnB, alA, alB; bf16x8 pa0, pa1, pa2, pa3; const int NT = seq / 64;
;   constexpr int SE = 0, SO = SD - 1;
;   if (__builtin_amdgcn_readfirstlane(tid) >= 256) __builtin_amdgcn_s_setprio(1);
;   __syncthreads();
;     ...
;   SLOAD(SE, 0); asm volatile("s_waitcnt vmcnt(0)" ::: "memory"); SWRITE(0, SE); __syncthreads();
;   if constexpr (MI) { qkt_mi<NQK>(pA0, pA1, K_lds, qr, r32, hi, minit); decide_mi(pA0, pA1, minit, Mref, alA, thr2, true);
; #pragma unroll
;     for (int r = 0; r < 16; ++r) pA0[r] = __builtin_amdgcn_exp2f(pA0[r]); }
;   else { qkt<NQK>(pA0, pA1, K_lds, qr, r32, hi); partialSM(pA0, pA1, m_reg, mnA, alA, C, thr); }
;   SLOAD(SO, 64); if constexpr (SD == 2) { if (2 < NT) SLOAD(SE, 2 * 64); }
;   SWAIT(); SWRITE(1, SO); __syncthreads();
;   int rp = 0, rc = 1, rn = 2;
;     ...
;   for (int j = 1; j + 1 < NT; j += 2) {
;     SBAR(); QKT(pB0, pB1, K_lds + rc * KT);
	v_mfma_f32_32x32x16_bf16 v[64:79], v[222:225], v[96:99], v[64:79]
	v_max_f32_e32 v169, v180, v169
	v_max3_f32 v169, v169, v82, v83
	v_max3_f32 v169, v169, v84, v85
	v_max3_f32 v169, v169, v86, v87
	v_max3_f32 v169, v169, v88, v89
	v_max3_f32 v169, v169, v90, v91
	v_exp_f32_e32 v222, v159
	v_max3_f32 v169, v169, v92, v93
	v_exp_f32_e32 v223, v156
	v_max3_f32 v169, v169, v94, v95
	v_exp_f32_e32 v224, v157
	s_nop 0
	v_max3_f32 v169, v169, v64, v65
	v_exp_f32_e32 v225, v154
	v_max3_f32 v169, v169, v66, v67
	v_add_f32_e32 v146, v222, v146
	v_max3_f32 v169, v169, v68, v69
	v_add_f32_e32 v146, v223, v146
	v_max3_f32 v169, v169, v70, v71
	v_add_f32_e32 v146, v224, v146
	v_max3_f32 v169, v169, v72, v73
	v_add_f32_e32 v146, v225, v146
	v_max3_f32 v169, v169, v74, v75
	v_add_f32_e32 v146, v226, v146
	v_max3_f32 v169, v169, v76, v77
	v_add_f32_e32 v146, v227, v146
	v_max3_f32 v169, v169, v78, v79
	v_add_f32_e32 v146, v228, v146
	v_mov_b32_e32 v180, v169
	v_add_f32_e32 v146, v229, v146
	s_nop 0
	v_permlane32_swap_b32_e32 v169, v180
	v_add_f32_e32 v146, v230, v146
	v_max_f32_e32 v180, v180, v180
	v_max_f32_e32 v169, v169, v169
	v_add_f32_e32 v146, v148, v146
	v_max_f32_e32 v169, v169, v180
	v_add_f32_e32 v146, v149, v146
	v_sub_f32_e32 v180, v169, v178
	v_add_f32_e32 v146, v231, v146
	v_cmp_ge_f32_e32 vcc, s56, v180
	v_max_f32_e32 v180, v178, v178
	v_add_f32_e32 v181, v232, v146
	v_max_f32_e32 v180, v180, v169
	v_mov_b32_e32 v182, v181
	s_cmp_eq_u64 vcc, exec
	v_sub_f32_e32 v169, v178, v180
	v_permlane32_swap_b32_e32 v181, v182
	s_cselect_b64 s[8:9], -1, 0
	v_mul_f32_e32 v169, 0x3dd53b94, v169
	v_cvt_pk_bf16_f32 v159, v189, v191
	v_cvt_pk_bf16_f32 v154, v215, v218
	v_cvt_pk_bf16_f32 v156, v216, v219
	v_cvt_pk_bf16_f32 v157, v220, v221
	v_cvt_pk_bf16_f32 v151, v183, v222
	v_cvt_pk_bf16_f32 v152, v223, v224
	v_cvt_pk_bf16_f32 v153, v225, v226
	v_cvt_pk_bf16_f32 v146, v227, v228
	v_cvt_pk_bf16_f32 v148, v148, v149
	v_cvt_pk_bf16_f32 v149, v231, v232
	s_add_i32 s10, s13, 0xfffe8000
	s_mov_b32 s38, s30
	s_mov_b32 s39, s31
	s_add_i32 s11, s13, 0xffff0000
	buffer_load_dwordx4 v[198:201], v170, s[28:31], s10 offen
	buffer_load_dwordx4 v[214:217], v170, s[28:31], s11 offen
	buffer_load_dwordx4 v[218:221], v171, s[36:39], s12 offen
	buffer_load_dwordx4 v[222:225], v176, s[36:39], s12 offen
	buffer_load_dwordx4 v[226:229], v177, s[36:39], s12 offen
	v_exp_f32_e32 v183, v169
	s_lshl_b32 s16, s44, 14
	v_add_u32_e32 v169, s16, v168
	ds_read_b64_tr_b16 v[230:231], v169 offset:0
	ds_read_b64_tr_b16 v[232:233], v169 offset:0x800
	ds_read_b64_tr_b16 v[234:235], v169 offset:0x1000
	ds_read_b64_tr_b16 v[236:237], v169 offset:0x1800
	ds_read_b64_tr_b16 v[238:239], v169 offset:0x2000
	ds_read_b64_tr_b16 v[240:241], v169 offset:0x2800
	ds_read_b64_tr_b16 v[242:243], v169 offset:0x3000
	ds_read_b64_tr_b16 v[244:245], v169 offset:0x3800
	s_waitcnt lgkmcnt(6)
	s_nop 0
	v_mfma_f32_32x32x16_bf16 v[0:15], v[158:161], v[230:233], v[0:15]
	ds_read_b64_tr_b16 v[230:231], v169 offset:0x200
	ds_read_b64_tr_b16 v[232:233], v169 offset:0xa00
	s_waitcnt lgkmcnt(6)
	v_mfma_f32_32x32x16_bf16 v[0:15], v[154:157], v[234:237], v[0:15]
	ds_read_b64_tr_b16 v[234:235], v169 offset:0x1200
	ds_read_b64_tr_b16 v[236:237], v169 offset:0x1a00
	s_waitcnt lgkmcnt(6)
	v_mfma_f32_32x32x16_bf16 v[0:15], v[150:153], v[238:241], v[0:15]
	ds_read_b64_tr_b16 v[238:239], v169 offset:0x2200
	ds_read_b64_tr_b16 v[240:241], v169 offset:0x2a00
	s_waitcnt lgkmcnt(6)
	v_mfma_f32_32x32x16_bf16 v[0:15], v[146:149], v[242:245], v[0:15]
	ds_read_b64_tr_b16 v[242:243], v169 offset:0x3200
	ds_read_b64_tr_b16 v[244:245], v169 offset:0x3a00
	s_waitcnt lgkmcnt(6)
	v_mfma_f32_32x32x16_bf16 v[48:63], v[158:161], v[230:233], v[48:63]
	ds_read_b64_tr_b16 v[230:231], v169 offset:0x400
	ds_read_b64_tr_b16 v[232:233], v169 offset:0xc00
	s_waitcnt lgkmcnt(6)
	v_mfma_f32_32x32x16_bf16 v[48:63], v[154:157], v[234:237], v[48:63]
	ds_read_b64_tr_b16 v[234:235], v169 offset:0x1400
	ds_read_b64_tr_b16 v[236:237], v169 offset:0x1c00
	s_waitcnt lgkmcnt(6)
	v_mfma_f32_32x32x16_bf16 v[48:63], v[150:153], v[238:241], v[48:63]
	ds_read_b64_tr_b16 v[238:239], v169 offset:0x2400
	ds_read_b64_tr_b16 v[240:241], v169 offset:0x2c00
	s_waitcnt lgkmcnt(6)
	v_mfma_f32_32x32x16_bf16 v[48:63], v[146:149], v[242:245], v[48:63]
	ds_read_b64_tr_b16 v[242:243], v169 offset:0x3400
	ds_read_b64_tr_b16 v[244:245], v169 offset:0x3c00
	s_waitcnt lgkmcnt(6)
	v_mfma_f32_32x32x16_bf16 v[32:47], v[158:161], v[230:233], v[32:47]
	ds_read_b64_tr_b16 v[230:231], v169 offset:0x600
	ds_read_b64_tr_b16 v[232:233], v169 offset:0xe00
	s_waitcnt lgkmcnt(6)
	v_mfma_f32_32x32x16_bf16 v[32:47], v[154:157], v[234:237], v[32:47]
	ds_read_b64_tr_b16 v[234:235], v169 offset:0x1600
	ds_read_b64_tr_b16 v[236:237], v169 offset:0x1e00
	s_waitcnt lgkmcnt(6)
	v_mfma_f32_32x32x16_bf16 v[32:47], v[150:153], v[238:241], v[32:47]
	ds_read_b64_tr_b16 v[238:239], v169 offset:0x2600
	ds_read_b64_tr_b16 v[240:241], v169 offset:0x2e00
	s_waitcnt lgkmcnt(6)
	v_mfma_f32_32x32x16_bf16 v[32:47], v[146:149], v[242:245], v[32:47]
	ds_read_b64_tr_b16 v[242:243], v169 offset:0x3600
	ds_read_b64_tr_b16 v[244:245], v169 offset:0x3e00
	s_waitcnt lgkmcnt(6)
	v_mfma_f32_32x32x16_bf16 v[16:31], v[158:161], v[230:233], v[16:31]
	s_lshl_b32 s15, s51, 14
	s_mul_i32 s17, s51, 0x6400
	v_cndmask_b32_e64 v183, v183, 1.0, s[8:9]
	v_cmp_gt_f32_e32 vcc, 1.0, v183
	s_waitcnt lgkmcnt(4)
	v_mfma_f32_32x32x16_bf16 v[16:31], v[154:157], v[234:237], v[16:31]
	v_add_u32_e32 v154, s15, v175
	s_waitcnt vmcnt(4)
	ds_write_b128 v154, v[198:201]
	s_waitcnt vmcnt(3)
	ds_write_b128 v154, v[214:217] offset:8192
	s_waitcnt lgkmcnt(4)
	v_mfma_f32_32x32x16_bf16 v[16:31], v[150:153], v[238:241], v[16:31]
	v_add_u32_e32 v150, s17, v173
	s_waitcnt vmcnt(2)
	ds_write_b128 v150, v[218:221] offset:49152
	s_waitcnt vmcnt(1)
	ds_write_b128 v150, v[222:225] offset:49280
	s_waitcnt vmcnt(0)
	ds_write_b128 v150, v[226:229] offset:49408
	s_waitcnt lgkmcnt(5)
	v_mfma_f32_32x32x16_bf16 v[16:31], v[146:149], v[242:245], v[16:31]
	s_cbranch_vccz .LBB0_2543
; template <int NQK>
; __device__ __forceinline__ void qkt(f32x16& p0, f32x16& p1, const char* Ks, const bf16x8* qr, int r32, int hi) {
;   constexpr int KROW = NQK * 32 + 16;
;   p0 = f32x16{}; p1 = f32x16{};
; #pragma unroll
;   for (int d0 = 0; d0 < NQK; ++d0) { const int cb = (d0 * 16 + hi * 8) * 2;
;     bf16x8 b0 = *reinterpret_cast<const bf16x8*>(Ks + r32 * KROW + cb);
;     bf16x8 b1 = *reinterpret_cast<const bf16x8*>(Ks + (32 + r32) * KROW + cb);
;     p0 = __builtin_amdgcn_mfma_f32_32x32x16_bf16(b0, qr[d0], p0, 0, 0, 0);
;     p1 = __builtin_amdgcn_mfma_f32_32x32x16_bf16(b1, qr[d0], p1, 0, 0, 0); }
; }
; template <int D0> __device__ __forceinline__ void pv_one_sm(f32x16& od, int vb, bf16x8 pa0, bf16x8 pa1, bf16x8 pa2, bf16x8 pa3, f32x16& q0, f32x16& q1, const float C, const float mnC) {
;     ...
;   if (D0 < 2) {
; #pragma unroll
;     for (int r = 8 * D0; r < 8 * D0 + 8; ++r) q0[r] = __builtin_amdgcn_exp2f(fmaf(q0[r], C, mnC));
;   } else {
; #pragma unroll
;     for (int r = 8 * (D0 - 2); r < 8 * (D0 - 2) + 8; ++r) q1[r] = fmaf(q1[r], C, mnC);
;   }
	s_and_saveexec_b64 s[10:11], s[6:7]
	ds_write_b32 v166, v183 offset:128
	s_or_b64 exec, exec, s[10:11]
	s_waitcnt lgkmcnt(0)
	v_add_u32_e32 v158, v165, v162
	ds_read_b128 v[146:149], v158 offset:224
	ds_read_b128 v[150:153], v158 offset:192
	ds_read_b128 v[154:157], v158 offset:160
	ds_read_b128 v[158:161], v158 offset:128
	s_waitcnt lgkmcnt(3)
	v_pk_mul_f32 v[12:13], v[12:13], v[146:147]
	s_waitcnt lgkmcnt(2)
	v_pk_mul_f32 v[8:9], v[8:9], v[150:151]
	s_waitcnt lgkmcnt(1)
	v_pk_mul_f32 v[4:5], v[4:5], v[154:155]
	v_pk_mul_f32 v[14:15], v[14:15], v[148:149]
	v_pk_mul_f32 v[10:11], v[10:11], v[152:153]
	v_pk_mul_f32 v[6:7], v[6:7], v[156:157]
	s_waitcnt lgkmcnt(0)
	v_pk_mul_f32 v[2:3], v[2:3], v[160:161]
	v_pk_mul_f32 v[0:1], v[0:1], v[158:159]
	v_pk_mul_f32 v[60:61], v[60:61], v[146:147]
	v_pk_mul_f32 v[56:57], v[56:57], v[150:151]
	v_pk_mul_f32 v[52:53], v[52:53], v[154:155]
	v_pk_mul_f32 v[62:63], v[62:63], v[148:149]
	v_pk_mul_f32 v[58:59], v[58:59], v[152:153]
	v_pk_mul_f32 v[54:55], v[54:55], v[156:157]
	v_pk_mul_f32 v[50:51], v[50:51], v[160:161]
	v_pk_mul_f32 v[48:49], v[48:49], v[158:159]
	v_pk_mul_f32 v[44:45], v[44:45], v[146:147]
	v_pk_mul_f32 v[40:41], v[40:41], v[150:151]
	v_pk_mul_f32 v[36:37], v[36:37], v[154:155]
	v_pk_mul_f32 v[46:47], v[46:47], v[148:149]
	v_pk_mul_f32 v[42:43], v[42:43], v[152:153]
	v_pk_mul_f32 v[38:39], v[38:39], v[156:157]
	v_pk_mul_f32 v[34:35], v[34:35], v[160:161]
	v_pk_mul_f32 v[32:33], v[32:33], v[158:159]
	v_pk_mul_f32 v[28:29], v[28:29], v[146:147]
	v_pk_mul_f32 v[24:25], v[24:25], v[150:151]
	v_pk_mul_f32 v[20:21], v[20:21], v[154:155]
	v_pk_mul_f32 v[30:31], v[30:31], v[148:149]
	v_pk_mul_f32 v[26:27], v[26:27], v[152:153]
	v_pk_mul_f32 v[22:23], v[22:23], v[156:157]
	v_pk_mul_f32 v[18:19], v[18:19], v[160:161]
	v_pk_mul_f32 v[16:17], v[16:17], v[158:159]
.LBB0_2543:
	v_cndmask_b32_e64 v178, v180, v178, s[8:9]
	v_mul_f32_e32 v154, 0xbdd53b94, v178
	v_fmamk_f32 v80, v80, 0x3dd53b94, v154
	v_exp_f32_e32 v155, v80
	v_fmamk_f32 v80, v81, 0x3dd53b94, v154
	v_exp_f32_e32 v156, v80
	v_fmamk_f32 v80, v82, 0x3dd53b94, v154
	v_exp_f32_e32 v157, v80
	v_fmamk_f32 v80, v83, 0x3dd53b94, v154
	v_exp_f32_e32 v159, v80
	v_fmamk_f32 v80, v84, 0x3dd53b94, v154
	v_exp_f32_e32 v160, v80
	v_fmamk_f32 v80, v85, 0x3dd53b94, v154
	v_exp_f32_e32 v161, v80
	v_fmamk_f32 v80, v86, 0x3dd53b94, v154
	v_exp_f32_e32 v180, v80
	v_fmamk_f32 v80, v87, 0x3dd53b94, v154
	v_exp_f32_e32 v189, v80
	v_fmamk_f32 v80, v88, 0x3dd53b94, v154
	v_exp_f32_e32 v191, v80
	v_fmamk_f32 v80, v89, 0x3dd53b94, v154
	v_exp_f32_e32 v198, v80
	v_fmamk_f32 v80, v90, 0x3dd53b94, v154
	v_exp_f32_e32 v199, v80
	v_fmamk_f32 v80, v91, 0x3dd53b94, v154
	v_exp_f32_e32 v200, v80
	v_fmamk_f32 v80, v92, 0x3dd53b94, v154
	v_exp_f32_e32 v201, v80
	v_fmamk_f32 v80, v93, 0x3dd53b94, v154
	v_exp_f32_e32 v214, v80
	v_fmamk_f32 v80, v94, 0x3dd53b94, v154
	v_exp_f32_e32 v215, v80
	v_fmamk_f32 v80, v95, 0x3dd53b94, v154
	v_fmamk_f32 v184, v66, 0x3dd53b94, v154
	v_fmamk_f32 v185, v68, 0x3dd53b94, v154
	v_exp_f32_e32 v216, v80
	v_fmamk_f32 v158, v64, 0x3dd53b94, v154
	v_fmamk_f32 v217, v70, 0x3dd53b94, v154
	v_fmamk_f32 v218, v65, 0x3dd53b94, v154
	v_fmamk_f32 v219, v67, 0x3dd53b94, v154
	v_fmamk_f32 v220, v69, 0x3dd53b94, v154
	v_fmamk_f32 v221, v71, 0x3dd53b94, v154
	v_fmamk_f32 v222, v72, 0x3dd53b94, v154
	v_fmamk_f32 v223, v73, 0x3dd53b94, v154
	v_fmamk_f32 v224, v74, 0x3dd53b94, v154
	v_fmamk_f32 v225, v75, 0x3dd53b94, v154
	v_fmamk_f32 v226, v76, 0x3dd53b94, v154
	v_fmamk_f32 v227, v77, 0x3dd53b94, v154
	v_fmamk_f32 v228, v78, 0x3dd53b94, v154
	v_fmac_f32_e32 v154, 0x3dd53b94, v79
	s_waitcnt lgkmcnt(0)
	s_barrier
	v_add_u32_e32 v229, s17, v174
	ds_read_b128 v[64:67], v229 offset:61952
	ds_read_b128 v[68:71], v229 offset:49152
	ds_read_b128 v[146:149], v229 offset:49184
	ds_read_b128 v[150:153], v229 offset:61984
	v_exp_f32_e32 v217, v217
	s_waitcnt lgkmcnt(2)
	v_mfma_f32_32x32x16_bf16 v[80:95], v[68:71], v[140:143], 0
	v_mfma_f32_32x32x16_bf16 v[64:79], v[64:67], v[140:143], 0
	s_waitcnt lgkmcnt(1)
	v_mfma_f32_32x32x16_bf16 v[80:95], v[146:149], v[136:139], v[80:95]
	s_waitcnt lgkmcnt(0)
	v_mfma_f32_32x32x16_bf16 v[64:79], v[150:153], v[136:139], v[64:79]
	ds_read_b128 v[146:149], v229 offset:49216
	ds_read_b128 v[150:153], v229 offset:62016
	s_waitcnt lgkmcnt(1)
	v_mfma_f32_32x32x16_bf16 v[80:95], v[146:149], v[132:135], v[80:95]
	s_waitcnt lgkmcnt(0)
	v_mfma_f32_32x32x16_bf16 v[64:79], v[150:153], v[132:135], v[64:79]
	ds_read_b128 v[146:149], v229 offset:49248
	ds_read_b128 v[150:153], v229 offset:62048
	s_waitcnt lgkmcnt(1)
	v_mfma_f32_32x32x16_bf16 v[80:95], v[146:149], v[128:131], v[80:95]
	s_waitcnt lgkmcnt(0)
	v_mfma_f32_32x32x16_bf16 v[64:79], v[150:153], v[128:131], v[64:79]
	ds_read_b128 v[146:149], v229 offset:49280
	ds_read_b128 v[150:153], v229 offset:62080
	s_waitcnt lgkmcnt(1)
	v_mfma_f32_32x32x16_bf16 v[80:95], v[146:149], v[124:127], v[80:95]
	s_waitcnt lgkmcnt(0)
	v_mfma_f32_32x32x16_bf16 v[64:79], v[150:153], v[124:127], v[64:79]
	ds_read_b128 v[146:149], v229 offset:49312
	ds_read_b128 v[150:153], v229 offset:62112
	s_waitcnt lgkmcnt(1)
	v_mfma_f32_32x32x16_bf16 v[80:95], v[146:149], v[120:123], v[80:95]
	s_waitcnt lgkmcnt(0)
	v_mfma_f32_32x32x16_bf16 v[64:79], v[150:153], v[120:123], v[64:79]
	ds_read_b128 v[146:149], v229 offset:49344
	ds_read_b128 v[150:153], v229 offset:62144
	s_waitcnt lgkmcnt(1)
	v_mfma_f32_32x32x16_bf16 v[80:95], v[146:149], v[116:119], v[80:95]
	s_waitcnt lgkmcnt(0)
	v_mfma_f32_32x32x16_bf16 v[64:79], v[150:153], v[116:119], v[64:79]
	ds_read_b128 v[146:149], v229 offset:49376
	ds_read_b128 v[150:153], v229 offset:62176
	s_waitcnt lgkmcnt(1)
; #define SBAR() __builtin_amdgcn_sched_barrier(0)
; __device__ __forceinline__ void decideSM(const f32x16& p0, const f32x16& p1, float& m_reg, float& mn, float& alpha, const float C, const float thr) {
;   float pmax = p0[0];
; #pragma unroll
;   for (int r = 1; r < 16; ++r) pmax = fmaxf(pmax, p0[r]);
; #pragma unroll
;   for (int r = 0; r < 16; ++r) pmax = fmaxf(pmax, p1[r]);
;   { auto rr = __builtin_amdgcn_permlane32_swap(__float_as_uint(pmax), __float_as_uint(pmax), false, false);
;     pmax = fmaxf(__uint_as_float(rr[0]), __uint_as_float(rr[1])); }
;   if (__builtin_expect(__all(pmax - m_reg <= thr), 1)) { mn = m_reg; alpha = 1.f; }
;   else { mn = fmaxf(m_reg, pmax); alpha = __builtin_amdgcn_exp2f((m_reg - mn) * C); m_reg = mn; }
; }
; __device__ __forceinline__ void finishSM(f32x16& p0, f32x16& p1, float alpha, float& l_reg, bf16x8& pa0, bf16x8& pa1, bf16x8& pa2, bf16x8& pa3) {
; #pragma unroll
;   for (int r = 0; r < 16; ++r) p1[r] = __builtin_amdgcn_exp2f(p1[r]);
;   float ps = 0;
; #pragma unroll
;   for (int r = 0; r < 16; ++r) ps += p0[r];
; #pragma unroll
;   for (int r = 0; r < 16; ++r) ps += p1[r];
;   { auto rr = __builtin_amdgcn_permlane32_swap(__float_as_uint(ps), __float_as_uint(ps), false, false);
;     ps = __uint_as_float(rr[0]) + __uint_as_float(rr[1]); }
;   l_reg = l_reg * alpha + ps;
;     ...
;   PK4(p0, 0, pa0); PK4(p0, 8, pa1); PK4(p1, 0, pa2); PK4(p1, 8, pa3);
;     ...
; }
; template <int D0> __device__ __forceinline__ void pv_one_sm(f32x16& od, int vb, bf16x8 pa0, bf16x8 pa1, bf16x8 pa2, bf16x8 pa3, f32x16& q0, f32x16& q1, const float C, const float mnC) {
;   const s16x4 l0 = tr_read<v_rd_off(D0, 0, 0)>(vb), h0 = tr_read<v_rd_off(D0, 0, 1)>(vb), l1 = tr_read<v_rd_off(D0, 1, 0)>(vb), h1 = tr_read<v_rd_off(D0, 1, 1)>(vb);
;   const s16x4 l2 = tr_read<v_rd_off(D0, 2, 0)>(vb), h2 = tr_read<v_rd_off(D0, 2, 1)>(vb), l3 = tr_read<v_rd_off(D0, 3, 0)>(vb), h3 = tr_read<v_rd_off(D0, 3, 1)>(vb);
;   asm volatile("s_waitcnt lgkmcnt(0)" ::: "memory"); SBAR();
;     ...
;   od = __builtin_amdgcn_mfma_f32_32x32x16_bf16(pa0, PK(l0, h0), od, 0, 0, 0);
;   od = __builtin_amdgcn_mfma_f32_32x32x16_bf16(pa1, PK(l1, h1), od, 0, 0, 0);
;   od = __builtin_amdgcn_mfma_f32_32x32x16_bf16(pa2, PK(l2, h2), od, 0, 0, 0);
;   od = __builtin_amdgcn_mfma_f32_32x32x16_bf16(pa3, PK(l3, h3), od, 0, 0, 0);
	v_mfma_f32_32x32x16_bf16 v[80:95], v[146:149], v[112:115], v[80:95]
	s_waitcnt lgkmcnt(0)
	v_mfma_f32_32x32x16_bf16 v[64:79], v[150:153], v[112:115], v[64:79]
	ds_read_b128 v[146:149], v229 offset:49408
	ds_read_b128 v[150:153], v229 offset:62208
	s_waitcnt lgkmcnt(1)
	v_mfma_f32_32x32x16_bf16 v[80:95], v[146:149], v[108:111], v[80:95]
	s_waitcnt lgkmcnt(0)
	v_mfma_f32_32x32x16_bf16 v[64:79], v[150:153], v[108:111], v[64:79]
	ds_read_b128 v[146:149], v229 offset:49440
	ds_read_b128 v[150:153], v229 offset:62240
	s_waitcnt lgkmcnt(1)
	v_mfma_f32_32x32x16_bf16 v[80:95], v[146:149], v[104:107], v[80:95]
	s_waitcnt lgkmcnt(0)
	v_mfma_f32_32x32x16_bf16 v[64:79], v[150:153], v[104:107], v[64:79]
	ds_read_b128 v[146:149], v229 offset:49472
	ds_read_b128 v[150:153], v229 offset:62272
	s_waitcnt lgkmcnt(1)
	v_mfma_f32_32x32x16_bf16 v[80:95], v[146:149], v[100:103], v[80:95]
	s_waitcnt lgkmcnt(0)
	v_mfma_f32_32x32x16_bf16 v[64:79], v[150:153], v[100:103], v[64:79]
	ds_read_b128 v[146:149], v229 offset:49504
	ds_read_b128 v[150:153], v229 offset:62304
	s_waitcnt lgkmcnt(1)
	v_mfma_f32_32x32x16_bf16 v[80:95], v[146:149], v[96:99], v[80:95]
	v_exp_f32_e32 v146, v158
	v_exp_f32_e32 v147, v218
	v_exp_f32_e32 v148, v184
	v_exp_f32_e32 v149, v219
	v_exp_f32_e32 v218, v221
	v_exp_f32_e32 v219, v222
	v_exp_f32_e32 v221, v224
	s_waitcnt lgkmcnt(0)
	v_mfma_f32_32x32x16_bf16 v[64:79], v[150:153], v[96:99], v[64:79]
	v_add_f32_e32 v150, 0, v155
	v_add_f32_e32 v150, v156, v150
	v_add_f32_e32 v150, v157, v150
	v_add_f32_e32 v150, v159, v150
	v_add_f32_e32 v150, v160, v150
	v_add_f32_e32 v150, v161, v150
	v_add_f32_e32 v150, v180, v150
	v_add_f32_e32 v150, v189, v150
	v_add_f32_e32 v150, v191, v150
	v_cvt_pk_bf16_f32 v160, v160, v161
	v_cvt_pk_bf16_f32 v161, v180, v189
	v_max_f32_e32 v180, v81, v81
	v_max_f32_e32 v189, v80, v80
	v_add_f32_e32 v150, v198, v150
	v_max_f32_e32 v180, v189, v180
	v_add_f32_e32 v150, v199, v150
	v_max3_f32 v180, v180, v82, v83
	v_add_f32_e32 v150, v200, v150
	v_max3_f32 v180, v180, v84, v85
	v_add_f32_e32 v150, v201, v150
	v_max3_f32 v180, v180, v86, v87
	v_add_f32_e32 v150, v214, v150
	v_max3_f32 v180, v180, v88, v89
	v_add_f32_e32 v150, v215, v150
	v_max3_f32 v180, v180, v90, v91
	v_add_f32_e32 v150, v216, v150
	v_max3_f32 v180, v180, v92, v93
	v_exp_f32_e32 v152, v185
	v_add_f32_e32 v150, v146, v150
	v_max3_f32 v180, v180, v94, v95
	v_exp_f32_e32 v153, v220
	v_add_f32_e32 v150, v147, v150
	v_max3_f32 v180, v180, v64, v65
	v_add_f32_e32 v150, v148, v150
	v_max3_f32 v180, v180, v66, v67
	v_add_f32_e32 v150, v149, v150
	v_max3_f32 v180, v180, v68, v69
	v_add_f32_e32 v150, v152, v150
	v_max3_f32 v180, v180, v70, v71
	v_exp_f32_e32 v220, v223
	v_add_f32_e32 v150, v153, v150
	v_max3_f32 v180, v180, v72, v73
	v_add_f32_e32 v150, v217, v150
	v_max3_f32 v180, v180, v74, v75
	v_exp_f32_e32 v222, v225
	v_add_f32_e32 v150, v218, v150
	v_max3_f32 v180, v180, v76, v77
	v_exp_f32_e32 v223, v226
	v_add_f32_e32 v150, v219, v150
	v_max3_f32 v180, v180, v78, v79
	v_exp_f32_e32 v224, v227
	v_add_f32_e32 v150, v220, v150
	v_mov_b32_e32 v189, v180
	v_exp_f32_e32 v225, v228
	v_add_f32_e32 v150, v221, v150
	v_permlane32_swap_b32_e32 v180, v189
	v_exp_f32_e32 v226, v154
	v_add_f32_e32 v150, v222, v150
	v_max_f32_e32 v189, v189, v189
	v_max_f32_e32 v180, v180, v180
	v_add_f32_e32 v150, v223, v150
	v_max_f32_e32 v180, v180, v189
	v_add_f32_e32 v150, v224, v150
	v_sub_f32_e32 v189, v180, v178
	v_add_f32_e32 v150, v225, v150
	v_cmp_ge_f32_e32 vcc, s56, v189
	v_max_f32_e32 v189, v178, v178
	v_add_f32_e32 v184, v226, v150
	v_max_f32_e32 v189, v189, v180
	v_mov_b32_e32 v185, v184
	s_cmp_eq_u64 vcc, exec
	v_sub_f32_e32 v180, v178, v189
	v_permlane32_swap_b32_e32 v184, v185
	s_cselect_b64 s[8:9], -1, 0
	v_mul_f32_e32 v180, 0x3dd53b94, v180
	v_cvt_pk_bf16_f32 v158, v155, v156
	v_cvt_pk_bf16_f32 v159, v157, v159
	v_cvt_pk_bf16_f32 v154, v191, v198
	v_cvt_pk_bf16_f32 v155, v199, v200
	v_cvt_pk_bf16_f32 v156, v201, v214
	v_cvt_pk_bf16_f32 v157, v215, v216
	v_cvt_pk_bf16_f32 v150, v146, v147
	v_cvt_pk_bf16_f32 v151, v148, v149
	v_cvt_pk_bf16_f32 v152, v152, v153
	v_cvt_pk_bf16_f32 v153, v217, v218
	v_cvt_pk_bf16_f32 v146, v219, v220
	v_cvt_pk_bf16_f32 v147, v221, v222
	v_cvt_pk_bf16_f32 v148, v223, v224
	v_cvt_pk_bf16_f32 v149, v225, v226
	s_add_i32 s10, s13, 0xffff8000
	s_add_i32 s11, s12, 0x18000
	s_mov_b32 s38, s30
	s_mov_b32 s39, s31
	buffer_load_dwordx4 v[198:201], v170, s[28:31], s10 offen
	buffer_load_dwordx4 v[214:217], v170, s[28:31], s13 offen
	buffer_load_dwordx4 v[218:221], v171, s[36:39], s11 offen
	buffer_load_dwordx4 v[222:225], v176, s[36:39], s11 offen
	buffer_load_dwordx4 v[226:229], v177, s[36:39], s11 offen
	v_exp_f32_e32 v180, v180
	v_lshl_add_u32 v191, s14, 14, v168
	ds_read_b64_tr_b16 v[230:231], v191 offset:0
	ds_read_b64_tr_b16 v[232:233], v191 offset:0x800
	ds_read_b64_tr_b16 v[234:235], v191 offset:0x1000
	ds_read_b64_tr_b16 v[236:237], v191 offset:0x1800
	ds_read_b64_tr_b16 v[238:239], v191 offset:0x2000
	ds_read_b64_tr_b16 v[240:241], v191 offset:0x2800
	ds_read_b64_tr_b16 v[242:243], v191 offset:0x3000
	ds_read_b64_tr_b16 v[244:245], v191 offset:0x3800
	s_waitcnt lgkmcnt(6)
; #define SBAR() __builtin_amdgcn_sched_barrier(0)
; template <int D0> __device__ __forceinline__ void pv_one_sm(f32x16& od, int vb, bf16x8 pa0, bf16x8 pa1, bf16x8 pa2, bf16x8 pa3, f32x16& q0, f32x16& q1, const float C, const float mnC) {
;   const s16x4 l0 = tr_read<v_rd_off(D0, 0, 0)>(vb), h0 = tr_read<v_rd_off(D0, 0, 1)>(vb), l1 = tr_read<v_rd_off(D0, 1, 0)>(vb), h1 = tr_read<v_rd_off(D0, 1, 1)>(vb);
;   const s16x4 l2 = tr_read<v_rd_off(D0, 2, 0)>(vb), h2 = tr_read<v_rd_off(D0, 2, 1)>(vb), l3 = tr_read<v_rd_off(D0, 3, 0)>(vb), h3 = tr_read<v_rd_off(D0, 3, 1)>(vb);
;   asm volatile("s_waitcnt lgkmcnt(0)" ::: "memory"); SBAR();
;     ...
;   od = __builtin_amdgcn_mfma_f32_32x32x16_bf16(pa0, PK(l0, h0), od, 0, 0, 0);
;   od = __builtin_amdgcn_mfma_f32_32x32x16_bf16(pa1, PK(l1, h1), od, 0, 0, 0);
;   od = __builtin_amdgcn_mfma_f32_32x32x16_bf16(pa2, PK(l2, h2), od, 0, 0, 0);
;   od = __builtin_amdgcn_mfma_f32_32x32x16_bf16(pa3, PK(l3, h3), od, 0, 0, 0);
	s_nop 0
	v_mfma_f32_32x32x16_bf16 v[0:15], v[158:161], v[230:233], v[0:15]
	ds_read_b64_tr_b16 v[230:231], v191 offset:0x200
	ds_read_b64_tr_b16 v[232:233], v191 offset:0xa00
	s_waitcnt lgkmcnt(6)
	v_mfma_f32_32x32x16_bf16 v[0:15], v[154:157], v[234:237], v[0:15]
	ds_read_b64_tr_b16 v[234:235], v191 offset:0x1200
	ds_read_b64_tr_b16 v[236:237], v191 offset:0x1a00
	s_waitcnt lgkmcnt(6)
	v_mfma_f32_32x32x16_bf16 v[0:15], v[150:153], v[238:241], v[0:15]
	ds_read_b64_tr_b16 v[238:239], v191 offset:0x2200
	ds_read_b64_tr_b16 v[240:241], v191 offset:0x2a00
	s_waitcnt lgkmcnt(6)
	v_mfma_f32_32x32x16_bf16 v[0:15], v[146:149], v[242:245], v[0:15]
	ds_read_b64_tr_b16 v[242:243], v191 offset:0x3200
	ds_read_b64_tr_b16 v[244:245], v191 offset:0x3a00
	s_waitcnt lgkmcnt(6)
	v_mfma_f32_32x32x16_bf16 v[48:63], v[158:161], v[230:233], v[48:63]
	ds_read_b64_tr_b16 v[230:231], v191 offset:0x400
	ds_read_b64_tr_b16 v[232:233], v191 offset:0xc00
	s_waitcnt lgkmcnt(6)
	v_mfma_f32_32x32x16_bf16 v[48:63], v[154:157], v[234:237], v[48:63]
	ds_read_b64_tr_b16 v[234:235], v191 offset:0x1400
	ds_read_b64_tr_b16 v[236:237], v191 offset:0x1c00
	s_waitcnt lgkmcnt(6)
	v_mfma_f32_32x32x16_bf16 v[48:63], v[150:153], v[238:241], v[48:63]
	ds_read_b64_tr_b16 v[238:239], v191 offset:0x2400
	ds_read_b64_tr_b16 v[240:241], v191 offset:0x2c00
	s_waitcnt lgkmcnt(6)
	v_mfma_f32_32x32x16_bf16 v[48:63], v[146:149], v[242:245], v[48:63]
	ds_read_b64_tr_b16 v[242:243], v191 offset:0x3400
	ds_read_b64_tr_b16 v[244:245], v191 offset:0x3c00
	s_waitcnt lgkmcnt(6)
	v_mfma_f32_32x32x16_bf16 v[32:47], v[158:161], v[230:233], v[32:47]
	ds_read_b64_tr_b16 v[230:231], v191 offset:0x600
	ds_read_b64_tr_b16 v[232:233], v191 offset:0xe00
	s_waitcnt lgkmcnt(6)
	v_mfma_f32_32x32x16_bf16 v[32:47], v[154:157], v[234:237], v[32:47]
	ds_read_b64_tr_b16 v[234:235], v191 offset:0x1600
	ds_read_b64_tr_b16 v[236:237], v191 offset:0x1e00
	s_waitcnt lgkmcnt(6)
	v_mfma_f32_32x32x16_bf16 v[32:47], v[150:153], v[238:241], v[32:47]
	ds_read_b64_tr_b16 v[238:239], v191 offset:0x2600
	ds_read_b64_tr_b16 v[240:241], v191 offset:0x2e00
	s_waitcnt lgkmcnt(6)
	v_mfma_f32_32x32x16_bf16 v[32:47], v[146:149], v[242:245], v[32:47]
	ds_read_b64_tr_b16 v[242:243], v191 offset:0x3600
	ds_read_b64_tr_b16 v[244:245], v191 offset:0x3e00
	s_waitcnt lgkmcnt(6)
	v_mfma_f32_32x32x16_bf16 v[16:31], v[158:161], v[230:233], v[16:31]
	v_cndmask_b32_e64 v180, v180, 1.0, s[8:9]
	v_cmp_gt_f32_e32 vcc, 1.0, v180
	s_waitcnt lgkmcnt(4)
	v_mfma_f32_32x32x16_bf16 v[16:31], v[154:157], v[234:237], v[16:31]
	v_add_u32_e32 v154, s16, v175
	s_mul_i32 s16, s44, 0x6400
	s_waitcnt vmcnt(4)
	ds_write_b128 v154, v[198:201]
	s_waitcnt vmcnt(3)
	ds_write_b128 v154, v[214:217] offset:8192
	s_waitcnt lgkmcnt(4)
	v_mfma_f32_32x32x16_bf16 v[16:31], v[150:153], v[238:241], v[16:31]
	v_add_u32_e32 v150, s16, v173
	s_waitcnt vmcnt(2)
	ds_write_b128 v150, v[218:221] offset:49152
	s_waitcnt vmcnt(1)
	ds_write_b128 v150, v[222:225] offset:49280
	s_waitcnt vmcnt(0)
	ds_write_b128 v150, v[226:229] offset:49408
	s_waitcnt lgkmcnt(5)
	v_mfma_f32_32x32x16_bf16 v[16:31], v[146:149], v[242:245], v[16:31]
	s_cbranch_vccz .LBB0_2547
	s_and_saveexec_b64 s[10:11], s[6:7]
	ds_write_b32 v166, v180 offset:128
	s_or_b64 exec, exec, s[10:11]
	s_waitcnt lgkmcnt(0)
	v_add_u32_e32 v158, v165, v162
	ds_read_b128 v[146:149], v158 offset:224
	ds_read_b128 v[150:153], v158 offset:192
	ds_read_b128 v[154:157], v158 offset:160
	ds_read_b128 v[158:161], v158 offset:128
	s_waitcnt lgkmcnt(3)
	v_pk_mul_f32 v[12:13], v[12:13], v[146:147]
	s_waitcnt lgkmcnt(2)
	v_pk_mul_f32 v[8:9], v[8:9], v[150:151]
	s_waitcnt lgkmcnt(1)
	v_pk_mul_f32 v[4:5], v[4:5], v[154:155]
	v_pk_mul_f32 v[14:15], v[14:15], v[148:149]
	v_pk_mul_f32 v[10:11], v[10:11], v[152:153]
	v_pk_mul_f32 v[6:7], v[6:7], v[156:157]
	s_waitcnt lgkmcnt(0)
	v_pk_mul_f32 v[2:3], v[2:3], v[160:161]
	v_pk_mul_f32 v[0:1], v[0:1], v[158:159]
	v_pk_mul_f32 v[60:61], v[60:61], v[146:147]
	v_pk_mul_f32 v[56:57], v[56:57], v[150:151]
	v_pk_mul_f32 v[52:53], v[52:53], v[154:155]
	v_pk_mul_f32 v[62:63], v[62:63], v[148:149]
	v_pk_mul_f32 v[58:59], v[58:59], v[152:153]
	v_pk_mul_f32 v[54:55], v[54:55], v[156:157]
	v_pk_mul_f32 v[50:51], v[50:51], v[160:161]
	v_pk_mul_f32 v[48:49], v[48:49], v[158:159]
	v_pk_mul_f32 v[44:45], v[44:45], v[146:147]
	v_pk_mul_f32 v[40:41], v[40:41], v[150:151]
	v_pk_mul_f32 v[36:37], v[36:37], v[154:155]
	v_pk_mul_f32 v[46:47], v[46:47], v[148:149]
	v_pk_mul_f32 v[42:43], v[42:43], v[152:153]
	v_pk_mul_f32 v[38:39], v[38:39], v[156:157]
	v_pk_mul_f32 v[34:35], v[34:35], v[160:161]
	v_pk_mul_f32 v[32:33], v[32:33], v[158:159]
	v_pk_mul_f32 v[28:29], v[28:29], v[146:147]
	v_pk_mul_f32 v[24:25], v[24:25], v[150:151]
	v_pk_mul_f32 v[20:21], v[20:21], v[154:155]
	v_pk_mul_f32 v[30:31], v[30:31], v[148:149]
	v_pk_mul_f32 v[26:27], v[26:27], v[152:153]
	v_pk_mul_f32 v[22:23], v[22:23], v[156:157]
	v_pk_mul_f32 v[18:19], v[18:19], v[160:161]
	v_pk_mul_f32 v[16:17], v[16:17], v[158:159]
